# up/gate GEMM (swiglu) epilogue: item pairs exchanged with v_permlane16_swap and stored as 4 dwordx4 (64 B row fragments) instead of 8 dwordx2 (32 B fragments)
# speedup vs baseline: 1.0154x; 1.0068x over previous
; DI float frcp(float x) { return __builtin_amdgcn_rcpf(x); }
;     __device__ __forceinline__ void operator()(const f32x4 (&acc)[2][2][4][2], const Unit& u, int wr, int wc, int fr, int fq) const {
;         const int row0 = u.pm * BM + wr * 64 + fr, col0 = (u.pn & 15) * 128 + wc * 32 + 8 * fq;
; #pragma unroll
;         for (int ai = 0; ai < 2; ++ai)
; #pragma unroll
;             for (int m = 0; m < 4; ++m) { const f32x4 g0 = acc[ai][0][m][0], g1 = acc[ai][0][m][1], u0 = acc[ai][1][m][0], u1 = acc[ai][1][m][1];
;                 f32x4 h0, h1;
; #pragma unroll
;                 for (int j = 0; j < 4; ++j) { const float t0 = __builtin_amdgcn_exp2f(g0[j] * (-0.03125f * 1.44269504088896f)), t1 = __builtin_amdgcn_exp2f(g1[j] * (-0.03125f * 1.44269504088896f));
;                     h0[j] = g0[j] * u0[j] * frcp(__builtin_fmaf(t0, 1024.0f, 1024.0f)); h1[j] = g1[j] * u1[j] * frcp(__builtin_fmaf(t1, 1024.0f, 1024.0f)); }
;                 u32x2 w; w.x = pk4_fp8(h0[0], h0[1], h0[2], h0[3]); w.y = pk4_fp8(h1[0], h1[1], h1[2], h1[3]);
;                 int rowi = row0 + ai * HALF + m * 16; asm volatile("" : "+v"(rowi));
;                 *(u32x2*)(HID + (size_t)rowi * DE + col0) = w; asm volatile("" ::: "memory"); }
.LBB0_1521:
	v_and_b32_e32 v240, 16, v212
	v_lshlrev_b32_e32 v248, 11, v240
	v_lshrrev_b32_e32 v240, 1, v240
	v_sub_u32_e32 v248, v248, v240
	v_mov_b32_e32 v249, 0
	v_mul_f32_e32 v5, 0xbd38aa3b, v140
	v_exp_f32_e32 v5, v5
	v_mul_f32_e32 v6, 0xbd38aa3b, v136
	v_exp_f32_e32 v6, v6
	v_mul_f32_e32 v7, v144, v140
	v_fmamk_f32 v5, v5, 0x44800000, v215
	v_rcp_f32_e32 v5, v5
	v_fmamk_f32 v6, v6, 0x44800000, v215
	v_rcp_f32_e32 v6, v6
	v_mul_f32_e32 v9, v145, v141
	v_mul_f32_e32 v5, v7, v5
	v_mul_f32_e32 v7, v132, v136
	v_mul_f32_e32 v8, v7, v6
	v_mul_f32_e32 v6, 0xbd38aa3b, v141
	v_exp_f32_e32 v6, v6
	v_mul_f32_e32 v7, 0xbd38aa3b, v137
	v_exp_f32_e32 v7, v7
	v_mul_f32_e32 v10, 0xbd38aa3b, v142
	v_fmamk_f32 v6, v6, 0x44800000, v215
	v_rcp_f32_e32 v6, v6
	v_fmamk_f32 v7, v7, 0x44800000, v215
	v_rcp_f32_e32 v7, v7
	v_exp_f32_e32 v10, v10
	v_mul_f32_e32 v9, v9, v6
	v_mul_f32_e32 v6, v133, v137
	v_mul_f32_e32 v11, v6, v7
	v_mul_f32_e32 v7, 0xbd38aa3b, v138
	v_exp_f32_e32 v7, v7
	v_mul_f32_e32 v12, 0xbd38aa3b, v143
	v_exp_f32_e32 v12, v12
	v_fmamk_f32 v6, v10, 0x44800000, v215
	v_rcp_f32_e32 v6, v6
	v_fmamk_f32 v7, v7, 0x44800000, v215
	v_rcp_f32_e32 v7, v7
	v_mul_f32_e32 v13, 0xbd38aa3b, v139
	v_fmamk_f32 v12, v12, 0x44800000, v215
	v_rcp_f32_e32 v12, v12
	v_exp_f32_e32 v13, v13
	v_mul_f32_e32 v10, v146, v142
	v_mul_f32_e32 v10, v10, v6
	v_mul_f32_e32 v6, v134, v138
	v_mov_b32_e32 v2, v1
	v_mul_f32_e32 v14, v6, v7
	v_mul_f32_e32 v6, v147, v143
	s_nop 15
	s_nop 15
	s_nop 15
	v_mul_f32_e32 v12, v6, v12
	v_readfirstlane_b32 s20, v2
	v_fmamk_f32 v6, v13, 0x44800000, v215
	s_ashr_i32 s22, s20, 2
	v_rcp_f32_e32 v13, v6
	v_mov_b32_e32 v6, v3
	v_mov_b32_e32 v7, v3
	s_lshl_b32 s21, s57, 8
	s_andn2_b32 s22, s22, 63
	v_cvt_pk_fp8_f32 v6, v5, v9
	v_cvt_pk_fp8_f32 v7, v8, v11
	s_add_i32 s22, s22, s21
	v_and_or_b32 v4, v2, 15, s22
	v_mul_f32_e32 v5, v135, v139
	s_lshl_b32 s21, s56, 7
	v_mul_f32_e32 v5, v5, v13
	v_mov_b32_e32 v8, v4
	s_and_b32 s21, s21, 0x780
	s_lshr_b32 s20, s20, 1
	v_lshrrev_b32_e32 v2, 1, v2
	v_cvt_pk_fp8_f32 v6, v10, v12 op_sel:[0,0,1]
	v_cvt_pk_fp8_f32 v7, v14, v5 op_sel:[0,0,1]
	s_and_b32 s20, s20, 0x60
	v_ashrrev_i32_e32 v9, 31, v8
	v_and_or_b32 v2, v2, 24, s21
	v_lshlrev_b64 v[8:9], 11, v[8:9]
	v_or_b32_e32 v2, s20, v2
	v_lshl_add_u64 v[8:9], s[10:11], 0, v[8:9]
	v_lshl_add_u64 v[8:9], v[8:9], 0, v[2:3]
	v_mul_f32_e32 v5, 0xbd38aa3b, v128
	v_mov_b32_e32 v242, v6
	v_mov_b32_e32 v243, v7
	v_mov_b32_e32 v246, v8
	v_mov_b32_e32 v247, v9
	v_exp_f32_e32 v5, v5
	v_mul_f32_e32 v6, 0xbd38aa3b, v120
	v_exp_f32_e32 v6, v6
	v_mul_f32_e32 v7, v124, v128
	v_fmamk_f32 v5, v5, 0x44800000, v215
	v_rcp_f32_e32 v5, v5
	v_fmamk_f32 v6, v6, 0x44800000, v215
	v_rcp_f32_e32 v6, v6
	v_mul_f32_e32 v9, v125, v129
	v_mul_f32_e32 v5, v7, v5
	v_mul_f32_e32 v7, v116, v120
	v_mul_f32_e32 v8, v7, v6
	v_mul_f32_e32 v6, 0xbd38aa3b, v129
	v_exp_f32_e32 v6, v6
	v_mul_f32_e32 v7, 0xbd38aa3b, v121
	v_exp_f32_e32 v7, v7
	v_mul_f32_e32 v10, 0xbd38aa3b, v130
	v_fmamk_f32 v6, v6, 0x44800000, v215
	v_rcp_f32_e32 v6, v6
	v_fmamk_f32 v7, v7, 0x44800000, v215
	v_rcp_f32_e32 v7, v7
	v_exp_f32_e32 v10, v10
	v_mul_f32_e32 v9, v9, v6
	v_mul_f32_e32 v6, v117, v121
	v_mul_f32_e32 v11, v6, v7
	v_mul_f32_e32 v7, 0xbd38aa3b, v122
	v_exp_f32_e32 v7, v7
	v_mul_f32_e32 v12, 0xbd38aa3b, v131
	v_exp_f32_e32 v12, v12
	v_fmamk_f32 v6, v10, 0x44800000, v215
	v_rcp_f32_e32 v6, v6
	v_fmamk_f32 v7, v7, 0x44800000, v215
	v_rcp_f32_e32 v7, v7
	v_mul_f32_e32 v13, 0xbd38aa3b, v123
	v_fmamk_f32 v12, v12, 0x44800000, v215
	v_rcp_f32_e32 v12, v12
	v_exp_f32_e32 v13, v13
	v_mul_f32_e32 v10, v126, v130
	v_mul_f32_e32 v10, v10, v6
	v_mul_f32_e32 v6, v118, v122
	v_mul_f32_e32 v14, v6, v7
	v_mul_f32_e32 v6, v127, v131
	v_mul_f32_e32 v12, v6, v12
	v_fmamk_f32 v6, v13, 0x44800000, v215
	v_rcp_f32_e32 v13, v6
	v_mov_b32_e32 v6, v3
	v_mov_b32_e32 v7, v3
	v_cvt_pk_fp8_f32 v6, v5, v9
	v_cvt_pk_fp8_f32 v7, v8, v11
	v_mul_f32_e32 v5, v119, v123
	v_mul_f32_e32 v5, v5, v13
	v_or_b32_e32 v8, 16, v4
	v_cvt_pk_fp8_f32 v6, v10, v12 op_sel:[0,0,1]
	v_cvt_pk_fp8_f32 v7, v14, v5 op_sel:[0,0,1]
	v_mul_f32_e32 v5, 0xbd38aa3b, v112
	v_ashrrev_i32_e32 v9, 31, v8
	v_lshlrev_b64 v[8:9], 11, v[8:9]
	v_lshl_add_u64 v[8:9], s[10:11], 0, v[8:9]
	v_lshl_add_u64 v[8:9], v[8:9], 0, v[2:3]
	v_mov_b32_e32 v244, v6
	v_mov_b32_e32 v245, v7
	v_lshl_add_u64 v[246:247], v[246:247], 0, v[248:249]
	s_nop 0
	v_permlane16_swap_b32_e32 v242, v244
	v_permlane16_swap_b32_e32 v243, v245
	global_store_dwordx4 v[246:247], v[242:245], off
	v_exp_f32_e32 v5, v5
	v_mul_f32_e32 v6, 0xbd38aa3b, v104
	v_exp_f32_e32 v6, v6
	v_mul_f32_e32 v7, v108, v112
	v_fmamk_f32 v5, v5, 0x44800000, v215
	v_rcp_f32_e32 v5, v5
	v_fmamk_f32 v6, v6, 0x44800000, v215
	v_rcp_f32_e32 v6, v6
	v_mul_f32_e32 v9, v109, v113
	v_mul_f32_e32 v5, v7, v5
	v_mul_f32_e32 v7, v100, v104
	v_mul_f32_e32 v8, v7, v6
	v_mul_f32_e32 v6, 0xbd38aa3b, v113
	v_exp_f32_e32 v6, v6
	v_mul_f32_e32 v7, 0xbd38aa3b, v105
	v_exp_f32_e32 v7, v7
	v_mul_f32_e32 v10, 0xbd38aa3b, v114
	v_fmamk_f32 v6, v6, 0x44800000, v215
	v_rcp_f32_e32 v6, v6
	v_fmamk_f32 v7, v7, 0x44800000, v215
	v_rcp_f32_e32 v7, v7
	v_exp_f32_e32 v10, v10
	v_mul_f32_e32 v9, v9, v6
	v_mul_f32_e32 v6, v101, v105
	v_mul_f32_e32 v11, v6, v7
	v_mul_f32_e32 v7, 0xbd38aa3b, v106
	v_exp_f32_e32 v7, v7
	v_mul_f32_e32 v12, 0xbd38aa3b, v115
	v_exp_f32_e32 v12, v12
	v_fmamk_f32 v6, v10, 0x44800000, v215
	v_rcp_f32_e32 v6, v6
	v_fmamk_f32 v7, v7, 0x44800000, v215
	v_rcp_f32_e32 v7, v7
	v_mul_f32_e32 v13, 0xbd38aa3b, v107
	v_fmamk_f32 v12, v12, 0x44800000, v215
	v_rcp_f32_e32 v12, v12
	v_exp_f32_e32 v13, v13
	v_mul_f32_e32 v10, v110, v114
	v_mul_f32_e32 v10, v10, v6
; DI float frcp(float x) { return __builtin_amdgcn_rcpf(x); }
;     __device__ __forceinline__ void operator()(const f32x4 (&acc)[2][2][4][2], const Unit& u, int wr, int wc, int fr, int fq) const {
;         const int row0 = u.pm * BM + wr * 64 + fr, col0 = (u.pn & 15) * 128 + wc * 32 + 8 * fq;
; #pragma unroll
;         for (int ai = 0; ai < 2; ++ai)
; #pragma unroll
;             for (int m = 0; m < 4; ++m) { const f32x4 g0 = acc[ai][0][m][0], g1 = acc[ai][0][m][1], u0 = acc[ai][1][m][0], u1 = acc[ai][1][m][1];
;                 f32x4 h0, h1;
; #pragma unroll
;                 for (int j = 0; j < 4; ++j) { const float t0 = __builtin_amdgcn_exp2f(g0[j] * (-0.03125f * 1.44269504088896f)), t1 = __builtin_amdgcn_exp2f(g1[j] * (-0.03125f * 1.44269504088896f));
;                     h0[j] = g0[j] * u0[j] * frcp(__builtin_fmaf(t0, 1024.0f, 1024.0f)); h1[j] = g1[j] * u1[j] * frcp(__builtin_fmaf(t1, 1024.0f, 1024.0f)); }
;                 u32x2 w; w.x = pk4_fp8(h0[0], h0[1], h0[2], h0[3]); w.y = pk4_fp8(h1[0], h1[1], h1[2], h1[3]);
;                 int rowi = row0 + ai * HALF + m * 16; asm volatile("" : "+v"(rowi));
;                 *(u32x2*)(HID + (size_t)rowi * DE + col0) = w; asm volatile("" ::: "memory"); }
	v_mul_f32_e32 v6, v102, v106
	v_mul_f32_e32 v14, v6, v7
	v_mul_f32_e32 v6, v111, v115
	v_mul_f32_e32 v12, v6, v12
	v_fmamk_f32 v6, v13, 0x44800000, v215
	v_rcp_f32_e32 v13, v6
	v_mov_b32_e32 v6, v3
	v_mov_b32_e32 v7, v3
	v_cvt_pk_fp8_f32 v6, v5, v9
	v_cvt_pk_fp8_f32 v7, v8, v11
	v_mul_f32_e32 v5, v103, v107
	v_mul_f32_e32 v5, v5, v13
	v_or_b32_e32 v8, 32, v4
	v_cvt_pk_fp8_f32 v6, v10, v12 op_sel:[0,0,1]
	v_cvt_pk_fp8_f32 v7, v14, v5 op_sel:[0,0,1]
	v_mul_f32_e32 v5, 0xbd38aa3b, v96
	v_ashrrev_i32_e32 v9, 31, v8
	v_lshlrev_b64 v[8:9], 11, v[8:9]
	v_lshl_add_u64 v[8:9], s[10:11], 0, v[8:9]
	v_lshl_add_u64 v[8:9], v[8:9], 0, v[2:3]
	v_mov_b32_e32 v242, v6
	v_mov_b32_e32 v243, v7
	v_mov_b32_e32 v246, v8
	v_mov_b32_e32 v247, v9
	v_exp_f32_e32 v5, v5
	v_mul_f32_e32 v6, 0xbd38aa3b, v88
	v_exp_f32_e32 v6, v6
	v_mul_f32_e32 v7, v92, v96
	v_fmamk_f32 v5, v5, 0x44800000, v215
	v_rcp_f32_e32 v5, v5
	v_fmamk_f32 v6, v6, 0x44800000, v215
	v_rcp_f32_e32 v6, v6
	v_mul_f32_e32 v9, v93, v97
	v_mul_f32_e32 v5, v7, v5
	v_mul_f32_e32 v7, v84, v88
	v_mul_f32_e32 v8, v7, v6
	v_mul_f32_e32 v6, 0xbd38aa3b, v97
	v_exp_f32_e32 v6, v6
	v_mul_f32_e32 v7, 0xbd38aa3b, v89
	v_exp_f32_e32 v7, v7
	v_mul_f32_e32 v10, 0xbd38aa3b, v98
	v_fmamk_f32 v6, v6, 0x44800000, v215
	v_rcp_f32_e32 v6, v6
	v_fmamk_f32 v7, v7, 0x44800000, v215
	v_rcp_f32_e32 v7, v7
	v_exp_f32_e32 v10, v10
	v_mul_f32_e32 v9, v9, v6
	v_mul_f32_e32 v6, v85, v89
	v_mul_f32_e32 v11, v6, v7
	v_mul_f32_e32 v7, 0xbd38aa3b, v90
	v_exp_f32_e32 v7, v7
	v_mul_f32_e32 v12, 0xbd38aa3b, v99
	v_exp_f32_e32 v12, v12
	v_fmamk_f32 v6, v10, 0x44800000, v215
	v_rcp_f32_e32 v6, v6
	v_fmamk_f32 v7, v7, 0x44800000, v215
	v_rcp_f32_e32 v7, v7
	v_mul_f32_e32 v13, 0xbd38aa3b, v91
	v_fmamk_f32 v12, v12, 0x44800000, v215
	v_rcp_f32_e32 v12, v12
	v_exp_f32_e32 v13, v13
	v_mul_f32_e32 v10, v94, v98
	v_mul_f32_e32 v10, v10, v6
	v_mul_f32_e32 v6, v86, v90
	v_mul_f32_e32 v14, v6, v7
	v_mul_f32_e32 v6, v95, v99
	v_mul_f32_e32 v12, v6, v12
	v_fmamk_f32 v6, v13, 0x44800000, v215
	v_rcp_f32_e32 v13, v6
	v_mov_b32_e32 v6, v3
	v_mov_b32_e32 v7, v3
	v_cvt_pk_fp8_f32 v6, v5, v9
	v_cvt_pk_fp8_f32 v7, v8, v11
	v_mul_f32_e32 v5, v87, v91
	v_mul_f32_e32 v5, v5, v13
	v_or_b32_e32 v8, 48, v4
	v_cvt_pk_fp8_f32 v6, v10, v12 op_sel:[0,0,1]
	v_cvt_pk_fp8_f32 v7, v14, v5 op_sel:[0,0,1]
	v_mul_f32_e32 v5, 0xbd38aa3b, v80
	v_ashrrev_i32_e32 v9, 31, v8
	v_lshlrev_b64 v[8:9], 11, v[8:9]
	v_lshl_add_u64 v[8:9], s[10:11], 0, v[8:9]
	v_lshl_add_u64 v[8:9], v[8:9], 0, v[2:3]
	v_mov_b32_e32 v244, v6
	v_mov_b32_e32 v245, v7
	v_lshl_add_u64 v[246:247], v[246:247], 0, v[248:249]
	s_nop 0
	v_permlane16_swap_b32_e32 v242, v244
	v_permlane16_swap_b32_e32 v243, v245
	global_store_dwordx4 v[246:247], v[242:245], off
	v_exp_f32_e32 v5, v5
	v_mul_f32_e32 v6, 0xbd38aa3b, v72
	v_exp_f32_e32 v7, v6
	v_mul_f32_e32 v8, v76, v80
	v_fmamk_f32 v5, v5, 0x44800000, v215
	v_rcp_f32_e32 v5, v5
	v_fmamk_f32 v7, v7, 0x44800000, v215
	v_rcp_f32_e32 v7, v7
	v_mul_f32_e32 v9, 0xbd38aa3b, v73
	v_mul_f32_e32 v5, v8, v5
	v_mul_f32_e32 v8, v68, v72
	v_mul_f32_e32 v7, v8, v7
	v_mul_f32_e32 v8, 0xbd38aa3b, v81
	v_exp_f32_e32 v8, v8
	v_exp_f32_e32 v9, v9
	v_mul_f32_e32 v10, v77, v81
	v_mul_f32_e32 v11, 0xbd38aa3b, v82
	v_fmamk_f32 v8, v8, 0x44800000, v215
	v_rcp_f32_e32 v8, v8
	v_fmamk_f32 v9, v9, 0x44800000, v215
	v_rcp_f32_e32 v9, v9
	v_exp_f32_e32 v11, v11
	v_mul_f32_e32 v10, v10, v8
	v_mul_f32_e32 v8, v69, v73
	v_mul_f32_e32 v12, v8, v9
	v_mul_f32_e32 v9, 0xbd38aa3b, v74
	v_exp_f32_e32 v9, v9
	v_mul_f32_e32 v13, 0xbd38aa3b, v83
	v_exp_f32_e32 v13, v13
	v_fmamk_f32 v8, v11, 0x44800000, v215
	v_rcp_f32_e32 v8, v8
	v_fmamk_f32 v9, v9, 0x44800000, v215
	v_rcp_f32_e32 v9, v9
	v_mul_f32_e32 v14, 0xbd38aa3b, v75
	v_fmamk_f32 v13, v13, 0x44800000, v215
	v_rcp_f32_e32 v13, v13
	v_exp_f32_e32 v14, v14
	v_mul_f32_e32 v11, v78, v82
	v_mul_f32_e32 v11, v11, v8
	v_mul_f32_e32 v8, v70, v74
	v_mul_f32_e32 v15, v8, v9
	v_mul_f32_e32 v8, v79, v83
	v_mul_f32_e32 v13, v8, v13
	v_fmamk_f32 v8, v14, 0x44800000, v215
	v_rcp_f32_e32 v14, v8
	v_mov_b32_e32 v8, v3
	v_mov_b32_e32 v9, v3
	v_cvt_pk_fp8_f32 v8, v5, v10
	v_cvt_pk_fp8_f32 v9, v7, v12
	v_mul_f32_e32 v5, v71, v75
	v_add_u32_e32 v6, 0x80, v4
	v_mul_f32_e32 v5, v5, v14
	v_cvt_pk_fp8_f32 v8, v11, v13 op_sel:[0,0,1]
	v_cvt_pk_fp8_f32 v9, v15, v5 op_sel:[0,0,1]
	v_mul_f32_e32 v5, 0xbd38aa3b, v64
	v_ashrrev_i32_e32 v7, 31, v6
	v_lshlrev_b64 v[6:7], 11, v[6:7]
	v_lshl_add_u64 v[6:7], s[10:11], 0, v[6:7]
	v_lshl_add_u64 v[6:7], v[6:7], 0, v[2:3]
	v_mov_b32_e32 v242, v8
	v_mov_b32_e32 v243, v9
	v_mov_b32_e32 v246, v6
	v_mov_b32_e32 v247, v7
	v_exp_f32_e32 v5, v5
	v_mul_f32_e32 v6, 0xbd38aa3b, v56
	v_exp_f32_e32 v6, v6
	v_mul_f32_e32 v7, v60, v64
	v_fmamk_f32 v5, v5, 0x44800000, v215
	v_rcp_f32_e32 v5, v5
	v_fmamk_f32 v6, v6, 0x44800000, v215
	v_rcp_f32_e32 v6, v6
	v_mul_f32_e32 v9, v61, v65
	v_mul_f32_e32 v5, v7, v5
	v_mul_f32_e32 v7, v52, v56
	v_mul_f32_e32 v8, v7, v6
	v_mul_f32_e32 v6, 0xbd38aa3b, v65
	v_exp_f32_e32 v6, v6
	v_mul_f32_e32 v7, 0xbd38aa3b, v57
	v_exp_f32_e32 v7, v7
	v_mul_f32_e32 v10, 0xbd38aa3b, v66
	v_fmamk_f32 v6, v6, 0x44800000, v215
	v_rcp_f32_e32 v6, v6
	v_fmamk_f32 v7, v7, 0x44800000, v215
	v_rcp_f32_e32 v7, v7
	v_exp_f32_e32 v10, v10
	v_mul_f32_e32 v9, v9, v6
	v_mul_f32_e32 v6, v53, v57
	v_mul_f32_e32 v11, v6, v7
; DI float frcp(float x) { return __builtin_amdgcn_rcpf(x); }
;     __device__ __forceinline__ void operator()(const f32x4 (&acc)[2][2][4][2], const Unit& u, int wr, int wc, int fr, int fq) const {
;         const int row0 = u.pm * BM + wr * 64 + fr, col0 = (u.pn & 15) * 128 + wc * 32 + 8 * fq;
; #pragma unroll
;         for (int ai = 0; ai < 2; ++ai)
; #pragma unroll
;             for (int m = 0; m < 4; ++m) { const f32x4 g0 = acc[ai][0][m][0], g1 = acc[ai][0][m][1], u0 = acc[ai][1][m][0], u1 = acc[ai][1][m][1];
;                 f32x4 h0, h1;
; #pragma unroll
;                 for (int j = 0; j < 4; ++j) { const float t0 = __builtin_amdgcn_exp2f(g0[j] * (-0.03125f * 1.44269504088896f)), t1 = __builtin_amdgcn_exp2f(g1[j] * (-0.03125f * 1.44269504088896f));
;                     h0[j] = g0[j] * u0[j] * frcp(__builtin_fmaf(t0, 1024.0f, 1024.0f)); h1[j] = g1[j] * u1[j] * frcp(__builtin_fmaf(t1, 1024.0f, 1024.0f)); }
;                 u32x2 w; w.x = pk4_fp8(h0[0], h0[1], h0[2], h0[3]); w.y = pk4_fp8(h1[0], h1[1], h1[2], h1[3]);
;                 int rowi = row0 + ai * HALF + m * 16; asm volatile("" : "+v"(rowi));
;                 *(u32x2*)(HID + (size_t)rowi * DE + col0) = w; asm volatile("" ::: "memory"); }
	v_mul_f32_e32 v7, 0xbd38aa3b, v58
	v_exp_f32_e32 v7, v7
	v_mul_f32_e32 v12, 0xbd38aa3b, v67
	v_exp_f32_e32 v12, v12
	v_fmamk_f32 v6, v10, 0x44800000, v215
	v_rcp_f32_e32 v6, v6
	v_fmamk_f32 v7, v7, 0x44800000, v215
	v_rcp_f32_e32 v7, v7
	v_mul_f32_e32 v13, 0xbd38aa3b, v59
	v_fmamk_f32 v12, v12, 0x44800000, v215
	v_rcp_f32_e32 v12, v12
	v_exp_f32_e32 v13, v13
	v_mul_f32_e32 v10, v62, v66
	v_mul_f32_e32 v10, v10, v6
	v_mul_f32_e32 v6, v54, v58
	v_mul_f32_e32 v14, v6, v7
	v_mul_f32_e32 v6, v63, v67
	v_mul_f32_e32 v12, v6, v12
	v_fmamk_f32 v6, v13, 0x44800000, v215
	v_rcp_f32_e32 v13, v6
	v_mov_b32_e32 v6, v3
	v_mov_b32_e32 v7, v3
	v_cvt_pk_fp8_f32 v6, v5, v9
	v_cvt_pk_fp8_f32 v7, v8, v11
	v_mul_f32_e32 v5, v55, v59
	v_mul_f32_e32 v5, v5, v13
	v_add_u32_e32 v8, 0x90, v4
	v_cvt_pk_fp8_f32 v6, v10, v12 op_sel:[0,0,1]
	v_cvt_pk_fp8_f32 v7, v14, v5 op_sel:[0,0,1]
	v_mul_f32_e32 v5, 0xbd38aa3b, v48
	v_ashrrev_i32_e32 v9, 31, v8
	v_lshlrev_b64 v[8:9], 11, v[8:9]
	v_lshl_add_u64 v[8:9], s[10:11], 0, v[8:9]
	v_lshl_add_u64 v[8:9], v[8:9], 0, v[2:3]
	v_mov_b32_e32 v244, v6
	v_mov_b32_e32 v245, v7
	v_lshl_add_u64 v[246:247], v[246:247], 0, v[248:249]
	s_nop 0
	v_permlane16_swap_b32_e32 v242, v244
	v_permlane16_swap_b32_e32 v243, v245
	global_store_dwordx4 v[246:247], v[242:245], off
	v_exp_f32_e32 v5, v5
	v_mul_f32_e32 v6, 0xbd38aa3b, v40
	v_exp_f32_e32 v6, v6
	v_mul_f32_e32 v7, v44, v48
	v_fmamk_f32 v5, v5, 0x44800000, v215
	v_rcp_f32_e32 v5, v5
	v_fmamk_f32 v6, v6, 0x44800000, v215
	v_rcp_f32_e32 v6, v6
	v_mul_f32_e32 v9, v45, v49
	v_mul_f32_e32 v5, v7, v5
	v_mul_f32_e32 v7, v36, v40
	v_mul_f32_e32 v8, v7, v6
	v_mul_f32_e32 v6, 0xbd38aa3b, v49
	v_exp_f32_e32 v6, v6
	v_mul_f32_e32 v7, 0xbd38aa3b, v41
	v_exp_f32_e32 v7, v7
	v_mul_f32_e32 v10, 0xbd38aa3b, v50
	v_fmamk_f32 v6, v6, 0x44800000, v215
	v_rcp_f32_e32 v6, v6
	v_fmamk_f32 v7, v7, 0x44800000, v215
	v_rcp_f32_e32 v7, v7
	v_exp_f32_e32 v10, v10
	v_mul_f32_e32 v9, v9, v6
	v_mul_f32_e32 v6, v37, v41
	v_mul_f32_e32 v11, v6, v7
	v_mul_f32_e32 v7, 0xbd38aa3b, v42
	v_exp_f32_e32 v7, v7
	v_mul_f32_e32 v12, 0xbd38aa3b, v51
	v_exp_f32_e32 v12, v12
	v_fmamk_f32 v6, v10, 0x44800000, v215
	v_rcp_f32_e32 v6, v6
	v_fmamk_f32 v7, v7, 0x44800000, v215
	v_rcp_f32_e32 v7, v7
	v_mul_f32_e32 v13, 0xbd38aa3b, v43
	v_fmamk_f32 v12, v12, 0x44800000, v215
	v_rcp_f32_e32 v12, v12
	v_exp_f32_e32 v13, v13
	v_mul_f32_e32 v10, v46, v50
	v_mul_f32_e32 v10, v10, v6
	v_mul_f32_e32 v6, v38, v42
	v_mul_f32_e32 v14, v6, v7
	v_mul_f32_e32 v6, v47, v51
	v_mul_f32_e32 v12, v6, v12
	v_fmamk_f32 v6, v13, 0x44800000, v215
	v_rcp_f32_e32 v13, v6
	v_mov_b32_e32 v6, v3
	v_mov_b32_e32 v7, v3
	v_cvt_pk_fp8_f32 v6, v5, v9
	v_cvt_pk_fp8_f32 v7, v8, v11
	v_mul_f32_e32 v5, v39, v43
	v_mul_f32_e32 v5, v5, v13
	v_add_u32_e32 v8, 0xa0, v4
	v_cvt_pk_fp8_f32 v6, v10, v12 op_sel:[0,0,1]
	v_cvt_pk_fp8_f32 v7, v14, v5 op_sel:[0,0,1]
	v_mul_f32_e32 v5, 0xbd38aa3b, v32
	v_ashrrev_i32_e32 v9, 31, v8
	v_lshlrev_b64 v[8:9], 11, v[8:9]
	v_lshl_add_u64 v[8:9], s[10:11], 0, v[8:9]
	v_lshl_add_u64 v[8:9], v[8:9], 0, v[2:3]
	v_mov_b32_e32 v242, v6
	v_mov_b32_e32 v243, v7
	v_mov_b32_e32 v246, v8
	v_mov_b32_e32 v247, v9
	v_exp_f32_e32 v5, v5
	v_mul_f32_e32 v6, 0xbd38aa3b, v24
	v_exp_f32_e32 v6, v6
	v_mul_f32_e32 v7, v28, v32
	v_fmamk_f32 v5, v5, 0x44800000, v215
	v_rcp_f32_e32 v5, v5
	v_fmamk_f32 v6, v6, 0x44800000, v215
	v_rcp_f32_e32 v6, v6
	v_mul_f32_e32 v9, v29, v33
	v_mul_f32_e32 v5, v7, v5
	v_mul_f32_e32 v7, v20, v24
	v_mul_f32_e32 v8, v7, v6
	v_mul_f32_e32 v6, 0xbd38aa3b, v33
	v_exp_f32_e32 v6, v6
	v_mul_f32_e32 v7, 0xbd38aa3b, v25
	v_exp_f32_e32 v7, v7
	v_mul_f32_e32 v10, 0xbd38aa3b, v34
	v_fmamk_f32 v6, v6, 0x44800000, v215
	v_rcp_f32_e32 v6, v6
	v_fmamk_f32 v7, v7, 0x44800000, v215
	v_rcp_f32_e32 v7, v7
	v_exp_f32_e32 v10, v10
	v_mul_f32_e32 v9, v9, v6
	v_mul_f32_e32 v6, v21, v25
	v_mul_f32_e32 v11, v6, v7
	v_mul_f32_e32 v7, 0xbd38aa3b, v26
	v_exp_f32_e32 v7, v7
	v_mul_f32_e32 v12, 0xbd38aa3b, v35
	v_exp_f32_e32 v12, v12
	v_fmamk_f32 v6, v10, 0x44800000, v215
	v_rcp_f32_e32 v6, v6
	v_fmamk_f32 v7, v7, 0x44800000, v215
	v_rcp_f32_e32 v7, v7
	v_mul_f32_e32 v13, 0xbd38aa3b, v27
	v_fmamk_f32 v12, v12, 0x44800000, v215
	v_rcp_f32_e32 v12, v12
	v_exp_f32_e32 v13, v13
	v_mul_f32_e32 v10, v30, v34
	v_mul_f32_e32 v10, v10, v6
	v_mul_f32_e32 v6, v22, v26
	v_mul_f32_e32 v14, v6, v7
	v_mul_f32_e32 v6, v31, v35
	v_mul_f32_e32 v12, v6, v12
	v_fmamk_f32 v6, v13, 0x44800000, v215
	v_rcp_f32_e32 v13, v6
	v_mov_b32_e32 v6, v3
	v_mov_b32_e32 v7, v3
	v_cvt_pk_fp8_f32 v6, v5, v9
	v_cvt_pk_fp8_f32 v7, v8, v11
	v_mul_f32_e32 v5, v23, v27
	v_mul_f32_e32 v5, v5, v13
	v_add_u32_e32 v4, 0xb0, v4
	v_cvt_pk_fp8_f32 v6, v10, v12 op_sel:[0,0,1]
	v_cvt_pk_fp8_f32 v7, v14, v5 op_sel:[0,0,1]
	s_and_b64 vcc, exec, s[14:15]
	v_ashrrev_i32_e32 v5, 31, v4
	v_lshlrev_b64 v[4:5], 11, v[4:5]
	v_lshl_add_u64 v[4:5], s[10:11], 0, v[4:5]
	v_lshl_add_u64 v[4:5], v[4:5], 0, v[2:3]
	v_mov_b32_e32 v244, v6
	v_mov_b32_e32 v245, v7
	v_lshl_add_u64 v[246:247], v[246:247], 0, v[248:249]
	s_nop 0
	v_permlane16_swap_b32_e32 v242, v244
	v_permlane16_swap_b32_e32 v243, v245
	global_store_dwordx4 v[246:247], v[242:245], off
	s_mov_b32 s56, s55
	s_mov_b32 s57, s54
	s_mov_b32 s25, s55
	s_mov_b32 s24, s54
	s_mov_b64 s[22:23], s[18:19]
	s_mov_b64 s[20:21], s[16:17]
	s_cbranch_vccnz .LBB0_1538
